# adaLN GEMV loop software-pipelined (next 8-row batch requested before the FMAs), differential pass drain with the V fragment ring and counted waits
# speedup vs baseline: 1.0348x; 1.0023x over previous
; __global__ void __launch_bounds__(512, 2) fwd_kernel(Params p) {
;     ...
;         const float* wp = p.w_ada + (size_t)l * DM * 3 * DM + (size_t)(wave * 128) * 3 * DM + j;
;         float a0 = 0.f, a1 = 0.f, a2 = 0.f, a3 = 0.f;
; #pragma unroll 8
;         for (int k = 0; k < 128; ++k) { const float wv = wp[(size_t)k * 3 * DM]; const int kk = wave * 128 + k;
;             a0 += condL[kk] * wv; a1 += condL[DM + kk] * wv; a2 += condL[2 * DM + kk] * wv; a3 += condL[3 * DM + kk] * wv; }
.LBB0_9:
	v_lshl_add_u64 v[28:29], v[18:19], 0, s[8:9]
	v_add_co_u32_e64 v30, s[4:5], s2, v28
	global_load_dword v60, v[28:29], off
	s_nop 0
	v_addc_co_u32_e64 v31, s[4:5], 0, v29, s[4:5]
	v_add_co_u32_e64 v32, s[4:5], s14, v28
	s_nop 0
	s_nop 0
	v_addc_co_u32_e64 v33, s[4:5], 0, v29, s[4:5]
	v_add_co_u32_e64 v34, s[4:5], s15, v28
	s_add_u32 s8, s8, 0x18000
	s_nop 0
	v_addc_co_u32_e64 v35, s[4:5], 0, v29, s[4:5]
	v_add_co_u32_e64 v36, s[4:5], s17, v28
	s_addc_u32 s9, s9, 0
	s_nop 0
	v_addc_co_u32_e64 v37, s[4:5], 0, v29, s[4:5]
	v_add_co_u32_e64 v38, s[4:5], s18, v28
	s_nop 0
	s_nop 0
	v_addc_co_u32_e64 v39, s[4:5], 0, v29, s[4:5]
	v_add_co_u32_e64 v40, s[4:5], s19, v28
	s_nop 0
	s_nop 0
	v_addc_co_u32_e64 v41, s[4:5], 0, v29, s[4:5]
	v_add_co_u32_e64 v28, s[4:5], s20, v28
	s_nop 1
	v_addc_co_u32_e64 v29, s[4:5], 0, v29, s[4:5]
	global_load_dword v62, v[30:31], off
	global_load_dword v64, v[32:33], off
	global_load_dword v66, v[34:35], off
	global_load_dword v68, v[36:37], off
	global_load_dword v70, v[38:39], off
	global_load_dword v72, v[40:41], off
	global_load_dword v74, v[28:29], off
.Lada_loop:
	v_lshl_add_u64 v[28:29], v[18:19], 0, s[8:9]
	v_add_co_u32_e64 v30, s[4:5], s2, v28
	global_load_dword v80, v[28:29], off
	s_nop 0
	v_addc_co_u32_e64 v31, s[4:5], 0, v29, s[4:5]
	v_add_co_u32_e64 v32, s[4:5], s14, v28
	s_nop 0
	s_nop 0
	v_addc_co_u32_e64 v33, s[4:5], 0, v29, s[4:5]
	v_add_co_u32_e64 v34, s[4:5], s15, v28
	s_add_u32 s8, s8, 0x18000
	s_nop 0
	v_addc_co_u32_e64 v35, s[4:5], 0, v29, s[4:5]
	v_add_co_u32_e64 v36, s[4:5], s17, v28
	s_addc_u32 s9, s9, 0
	s_nop 0
	v_addc_co_u32_e64 v37, s[4:5], 0, v29, s[4:5]
	v_add_co_u32_e64 v38, s[4:5], s18, v28
	s_nop 0
	s_nop 0
	v_addc_co_u32_e64 v39, s[4:5], 0, v29, s[4:5]
	v_add_co_u32_e64 v40, s[4:5], s19, v28
	s_nop 0
	s_nop 0
	v_addc_co_u32_e64 v41, s[4:5], 0, v29, s[4:5]
	v_add_co_u32_e64 v28, s[4:5], s20, v28
	s_nop 1
	v_addc_co_u32_e64 v29, s[4:5], 0, v29, s[4:5]
	global_load_dword v82, v[30:31], off
	global_load_dword v84, v[32:33], off
	global_load_dword v86, v[34:35], off
	global_load_dword v88, v[36:37], off
	global_load_dword v90, v[38:39], off
	global_load_dword v92, v[40:41], off
	global_load_dword v94, v[28:29], off
	v_mov_b32_e32 v27, s23
	ds_read_b128 v[28:31], v27
	ds_read_b128 v[32:35], v27 offset:16
	ds_read_b128 v[36:39], v27 offset:4096
	ds_read_b128 v[40:43], v27 offset:4112
	ds_read_b128 v[44:47], v27 offset:8192
	ds_read_b128 v[48:51], v27 offset:8208
	ds_read_b128 v[52:55], v27 offset:12288
	ds_read_b128 v[56:59], v27 offset:12304
	s_waitcnt lgkmcnt(7)
	v_mov_b32_e32 v76, v28
	s_waitcnt lgkmcnt(5)
	v_mov_b32_e32 v77, v36
	s_waitcnt lgkmcnt(3)
	v_mov_b32_e32 v78, v44
	s_waitcnt lgkmcnt(1)
	v_mov_b32_e32 v79, v52
	v_mov_b32_e32 v36, v29
	v_mov_b32_e32 v52, v45
	v_mov_b32_e32 v28, v30
	v_mov_b32_e32 v29, v38
	v_mov_b32_e32 v38, v31
	v_mov_b32_e32 v30, v46
	v_mov_b32_e32 v31, v54
	v_mov_b32_e32 v54, v47
	v_mov_b32_e32 v44, v32
	v_mov_b32_e32 v45, v40
	v_mov_b32_e32 v46, v48
	s_waitcnt lgkmcnt(0)
	v_mov_b32_e32 v47, v56
	v_mov_b32_e32 v40, v33
	v_mov_b32_e32 v56, v49
	v_mov_b32_e32 v32, v34
	v_mov_b32_e32 v33, v42
	v_mov_b32_e32 v42, v35
	v_mov_b32_e32 v34, v50
	v_mov_b32_e32 v35, v58
	v_mov_b32_e32 v58, v51
	s_waitcnt vmcnt(15)
	v_pk_fma_f32 v[20:21], v[60:61], v[76:77], v[20:21] op_sel_hi:[0,1,1]
	v_pk_fma_f32 v[22:23], v[60:61], v[78:79], v[22:23] op_sel_hi:[0,1,1]
	s_waitcnt vmcnt(14)
	v_pk_fma_f32 v[20:21], v[62:63], v[36:37], v[20:21] op_sel_hi:[0,1,1]
	v_pk_fma_f32 v[22:23], v[62:63], v[52:53], v[22:23] op_sel_hi:[0,1,1]
	s_waitcnt vmcnt(13)
	v_pk_fma_f32 v[20:21], v[64:65], v[28:29], v[20:21] op_sel_hi:[0,1,1]
	v_pk_fma_f32 v[22:23], v[64:65], v[30:31], v[22:23] op_sel_hi:[0,1,1]
	s_waitcnt vmcnt(12)
	v_pk_fma_f32 v[20:21], v[66:67], v[38:39], v[20:21] op_sel_hi:[0,1,1]
	v_pk_fma_f32 v[22:23], v[66:67], v[54:55], v[22:23] op_sel_hi:[0,1,1]
	s_waitcnt vmcnt(11)
	v_pk_fma_f32 v[20:21], v[68:69], v[44:45], v[20:21] op_sel_hi:[0,1,1]
	v_pk_fma_f32 v[22:23], v[68:69], v[46:47], v[22:23] op_sel_hi:[0,1,1]
	s_waitcnt vmcnt(10)
	v_pk_fma_f32 v[20:21], v[70:71], v[40:41], v[20:21] op_sel_hi:[0,1,1]
	v_pk_fma_f32 v[22:23], v[70:71], v[56:57], v[22:23] op_sel_hi:[0,1,1]
	s_waitcnt vmcnt(9)
	v_pk_fma_f32 v[20:21], v[72:73], v[32:33], v[20:21] op_sel_hi:[0,1,1]
	v_pk_fma_f32 v[22:23], v[72:73], v[34:35], v[22:23] op_sel_hi:[0,1,1]
	s_waitcnt vmcnt(8)
	v_pk_fma_f32 v[20:21], v[74:75], v[42:43], v[20:21] op_sel_hi:[0,1,1]
	v_pk_fma_f32 v[22:23], v[74:75], v[58:59], v[22:23] op_sel_hi:[0,1,1]
	s_add_i32 s23, s23, 32
	s_cmp_eq_u32 s8, 0x180000
	s_cbranch_scc1 .Lada_last
; __global__ void __launch_bounds__(512, 2) fwd_kernel(Params p) {
;     ...
; #pragma unroll 8
;         for (int k = 0; k < 128; ++k) { const float wv = wp[(size_t)k * 3 * DM]; const int kk = wave * 128 + k;
;             a0 += condL[kk] * wv; a1 += condL[DM + kk] * wv; a2 += condL[2 * DM + kk] * wv; a3 += condL[3 * DM + kk] * wv; }
	v_lshl_add_u64 v[28:29], v[18:19], 0, s[8:9]
	v_add_co_u32_e64 v30, s[4:5], s2, v28
	global_load_dword v60, v[28:29], off
	s_nop 0
	v_addc_co_u32_e64 v31, s[4:5], 0, v29, s[4:5]
	v_add_co_u32_e64 v32, s[4:5], s14, v28
	s_nop 0
	s_nop 0
	v_addc_co_u32_e64 v33, s[4:5], 0, v29, s[4:5]
	v_add_co_u32_e64 v34, s[4:5], s15, v28
	s_add_u32 s8, s8, 0x18000
	s_nop 0
	v_addc_co_u32_e64 v35, s[4:5], 0, v29, s[4:5]
	v_add_co_u32_e64 v36, s[4:5], s17, v28
	s_addc_u32 s9, s9, 0
	s_nop 0
	v_addc_co_u32_e64 v37, s[4:5], 0, v29, s[4:5]
	v_add_co_u32_e64 v38, s[4:5], s18, v28
	s_nop 0
	s_nop 0
	v_addc_co_u32_e64 v39, s[4:5], 0, v29, s[4:5]
	v_add_co_u32_e64 v40, s[4:5], s19, v28
	s_nop 0
	s_nop 0
	v_addc_co_u32_e64 v41, s[4:5], 0, v29, s[4:5]
	v_add_co_u32_e64 v28, s[4:5], s20, v28
	s_nop 1
	v_addc_co_u32_e64 v29, s[4:5], 0, v29, s[4:5]
	global_load_dword v62, v[30:31], off
	global_load_dword v64, v[32:33], off
	global_load_dword v66, v[34:35], off
	global_load_dword v68, v[36:37], off
	global_load_dword v70, v[38:39], off
	global_load_dword v72, v[40:41], off
	global_load_dword v74, v[28:29], off
	v_mov_b32_e32 v27, s23
	ds_read_b128 v[28:31], v27
	ds_read_b128 v[32:35], v27 offset:16
	ds_read_b128 v[36:39], v27 offset:4096
	ds_read_b128 v[40:43], v27 offset:4112
	ds_read_b128 v[44:47], v27 offset:8192
	ds_read_b128 v[48:51], v27 offset:8208
	ds_read_b128 v[52:55], v27 offset:12288
	ds_read_b128 v[56:59], v27 offset:12304
	s_waitcnt lgkmcnt(7)
	v_mov_b32_e32 v76, v28
	s_waitcnt lgkmcnt(5)
	v_mov_b32_e32 v77, v36
	s_waitcnt lgkmcnt(3)
	v_mov_b32_e32 v78, v44
	s_waitcnt lgkmcnt(1)
	v_mov_b32_e32 v79, v52
	v_mov_b32_e32 v36, v29
	v_mov_b32_e32 v52, v45
	v_mov_b32_e32 v28, v30
	v_mov_b32_e32 v29, v38
	v_mov_b32_e32 v38, v31
	v_mov_b32_e32 v30, v46
	v_mov_b32_e32 v31, v54
	v_mov_b32_e32 v54, v47
	v_mov_b32_e32 v44, v32
	v_mov_b32_e32 v45, v40
	v_mov_b32_e32 v46, v48
	s_waitcnt lgkmcnt(0)
	v_mov_b32_e32 v47, v56
	v_mov_b32_e32 v40, v33
	v_mov_b32_e32 v56, v49
	v_mov_b32_e32 v32, v34
	v_mov_b32_e32 v33, v42
	v_mov_b32_e32 v42, v35
	v_mov_b32_e32 v34, v50
	v_mov_b32_e32 v35, v58
	v_mov_b32_e32 v58, v51
	s_waitcnt vmcnt(15)
	v_pk_fma_f32 v[20:21], v[80:81], v[76:77], v[20:21] op_sel_hi:[0,1,1]
	v_pk_fma_f32 v[22:23], v[80:81], v[78:79], v[22:23] op_sel_hi:[0,1,1]
	s_waitcnt vmcnt(14)
	v_pk_fma_f32 v[20:21], v[82:83], v[36:37], v[20:21] op_sel_hi:[0,1,1]
	v_pk_fma_f32 v[22:23], v[82:83], v[52:53], v[22:23] op_sel_hi:[0,1,1]
	s_waitcnt vmcnt(13)
	v_pk_fma_f32 v[20:21], v[84:85], v[28:29], v[20:21] op_sel_hi:[0,1,1]
	v_pk_fma_f32 v[22:23], v[84:85], v[30:31], v[22:23] op_sel_hi:[0,1,1]
	s_waitcnt vmcnt(12)
	v_pk_fma_f32 v[20:21], v[86:87], v[38:39], v[20:21] op_sel_hi:[0,1,1]
	v_pk_fma_f32 v[22:23], v[86:87], v[54:55], v[22:23] op_sel_hi:[0,1,1]
	s_waitcnt vmcnt(11)
	v_pk_fma_f32 v[20:21], v[88:89], v[44:45], v[20:21] op_sel_hi:[0,1,1]
	v_pk_fma_f32 v[22:23], v[88:89], v[46:47], v[22:23] op_sel_hi:[0,1,1]
	s_waitcnt vmcnt(10)
	v_pk_fma_f32 v[20:21], v[90:91], v[40:41], v[20:21] op_sel_hi:[0,1,1]
	v_pk_fma_f32 v[22:23], v[90:91], v[56:57], v[22:23] op_sel_hi:[0,1,1]
	s_waitcnt vmcnt(9)
	v_pk_fma_f32 v[20:21], v[92:93], v[32:33], v[20:21] op_sel_hi:[0,1,1]
	v_pk_fma_f32 v[22:23], v[92:93], v[34:35], v[22:23] op_sel_hi:[0,1,1]
	s_waitcnt vmcnt(8)
	v_pk_fma_f32 v[20:21], v[94:95], v[42:43], v[20:21] op_sel_hi:[0,1,1]
	v_pk_fma_f32 v[22:23], v[94:95], v[58:59], v[22:23] op_sel_hi:[0,1,1]
	s_add_i32 s23, s23, 32
	s_branch .Lada_loop
; __global__ void __launch_bounds__(512, 2) fwd_kernel(Params p) {
;     ...
;         for (int k = 0; k < 128; ++k) { const float wv = wp[(size_t)k * 3 * DM]; const int kk = wave * 128 + k;
;             a0 += condL[kk] * wv; a1 += condL[DM + kk] * wv; a2 += condL[2 * DM + kk] * wv; a3 += condL[3 * DM + kk] * wv; }
;         red[(wave * 4 + 0) * 64 + lane] = a0; red[(wave * 4 + 1) * 64 + lane] = a1; red[(wave * 4 + 2) * 64 + lane] = a2; red[(wave * 4 + 3) * 64 + lane] = a3;
;         __syncthreads();
;         if (tid < 256) { const int bb = tid >> 6; float s = 0.f;
; #pragma unroll
;             for (int w = 0; w < 8; ++w) s += red[(w * 4 + bb) * 64 + lane];
;             ada[(size_t)(l * NB + bb) * 3 * DM + j] = s + p.b_ada[l * 3 * DM + j]; }
.Lada_last:
	v_mov_b32_e32 v27, s23
	ds_read_b128 v[28:31], v27
	ds_read_b128 v[32:35], v27 offset:16
	ds_read_b128 v[36:39], v27 offset:4096
	ds_read_b128 v[40:43], v27 offset:4112
	ds_read_b128 v[44:47], v27 offset:8192
	ds_read_b128 v[48:51], v27 offset:8208
	ds_read_b128 v[52:55], v27 offset:12288
	ds_read_b128 v[56:59], v27 offset:12304
	s_waitcnt lgkmcnt(7)
	v_mov_b32_e32 v76, v28
	s_waitcnt lgkmcnt(5)
	v_mov_b32_e32 v77, v36
	s_waitcnt lgkmcnt(3)
	v_mov_b32_e32 v78, v44
	s_waitcnt lgkmcnt(1)
	v_mov_b32_e32 v79, v52
	v_mov_b32_e32 v36, v29
	v_mov_b32_e32 v52, v45
	v_mov_b32_e32 v28, v30
	v_mov_b32_e32 v29, v38
	v_mov_b32_e32 v38, v31
	v_mov_b32_e32 v30, v46
	v_mov_b32_e32 v31, v54
	v_mov_b32_e32 v54, v47
	v_mov_b32_e32 v44, v32
	v_mov_b32_e32 v45, v40
	v_mov_b32_e32 v46, v48
	s_waitcnt lgkmcnt(0)
	v_mov_b32_e32 v47, v56
	v_mov_b32_e32 v40, v33
	v_mov_b32_e32 v56, v49
	v_mov_b32_e32 v32, v34
	v_mov_b32_e32 v33, v42
	v_mov_b32_e32 v42, v35
	v_mov_b32_e32 v34, v50
	v_mov_b32_e32 v35, v58
	v_mov_b32_e32 v58, v51
	s_waitcnt vmcnt(7)
	v_pk_fma_f32 v[20:21], v[80:81], v[76:77], v[20:21] op_sel_hi:[0,1,1]
	v_pk_fma_f32 v[22:23], v[80:81], v[78:79], v[22:23] op_sel_hi:[0,1,1]
	s_waitcnt vmcnt(6)
	v_pk_fma_f32 v[20:21], v[82:83], v[36:37], v[20:21] op_sel_hi:[0,1,1]
	v_pk_fma_f32 v[22:23], v[82:83], v[52:53], v[22:23] op_sel_hi:[0,1,1]
	s_waitcnt vmcnt(5)
	v_pk_fma_f32 v[20:21], v[84:85], v[28:29], v[20:21] op_sel_hi:[0,1,1]
	v_pk_fma_f32 v[22:23], v[84:85], v[30:31], v[22:23] op_sel_hi:[0,1,1]
	s_waitcnt vmcnt(4)
	v_pk_fma_f32 v[20:21], v[86:87], v[38:39], v[20:21] op_sel_hi:[0,1,1]
	v_pk_fma_f32 v[22:23], v[86:87], v[54:55], v[22:23] op_sel_hi:[0,1,1]
	s_waitcnt vmcnt(3)
	v_pk_fma_f32 v[20:21], v[88:89], v[44:45], v[20:21] op_sel_hi:[0,1,1]
	v_pk_fma_f32 v[22:23], v[88:89], v[46:47], v[22:23] op_sel_hi:[0,1,1]
	s_waitcnt vmcnt(2)
	v_pk_fma_f32 v[20:21], v[90:91], v[40:41], v[20:21] op_sel_hi:[0,1,1]
	v_pk_fma_f32 v[22:23], v[90:91], v[56:57], v[22:23] op_sel_hi:[0,1,1]
	s_waitcnt vmcnt(1)
	v_pk_fma_f32 v[20:21], v[92:93], v[32:33], v[20:21] op_sel_hi:[0,1,1]
	v_pk_fma_f32 v[22:23], v[92:93], v[34:35], v[22:23] op_sel_hi:[0,1,1]
	s_waitcnt vmcnt(0)
	v_pk_fma_f32 v[20:21], v[94:95], v[42:43], v[20:21] op_sel_hi:[0,1,1]
	v_pk_fma_f32 v[22:23], v[94:95], v[58:59], v[22:23] op_sel_hi:[0,1,1]
	s_add_i32 s23, s23, 32
	v_lshl_add_u32 v18, v26, 2, s13
	ds_write2st64_b32 v18, v20, v21 offset0:64 offset1:65
	ds_write2st64_b32 v18, v22, v23 offset0:66 offset1:67
	s_waitcnt lgkmcnt(0)
	s_barrier
	s_and_saveexec_b64 s[4:5], vcc
	s_cbranch_execz .LBB0_5
	s_mul_i32 s8, s22, 0xc00
	v_add_u32_e32 v18, s8, v16
	v_readlane_b32 s40, v233, 10
	v_ashrrev_i32_e32 v19, 31, v18
	v_readlane_b32 s46, v233, 16
	v_readlane_b32 s47, v233, 17
	v_lshl_add_u32 v26, v26, 2, v1
	v_lshl_or_b32 v28, s22, 2, v24
	v_lshl_add_u64 v[18:19], v[18:19], 2, s[46:47]
	global_load_dword v30, v[18:19], off
	ds_read2st64_b32 v[18:19], v26 offset0:64 offset1:68
	ds_read2st64_b32 v[20:21], v26 offset0:72 offset1:76
	ds_read2st64_b32 v[22:23], v26 offset0:80 offset1:84
	ds_read2st64_b32 v[26:27], v26 offset0:88 offset1:92
	v_lshl_add_u32 v28, v28, 1, v28
	s_waitcnt lgkmcnt(3)
	v_add_f32_e32 v18, 0, v18
	v_add_f32_e32 v18, v18, v19
	s_waitcnt lgkmcnt(2)
	v_add_f32_e32 v18, v18, v20
	v_add_f32_e32 v18, v18, v21
	s_waitcnt lgkmcnt(1)
	v_add_f32_e32 v18, v18, v22
	v_ashrrev_i32_e32 v29, 31, v28
	v_readlane_b32 s24, v233, 0
	v_add_f32_e32 v18, v18, v23
	v_lshlrev_b64 v[28:29], 12, v[28:29]
	v_readlane_b32 s30, v233, 6
	v_readlane_b32 s31, v233, 7
	s_waitcnt lgkmcnt(0)
	v_add_f32_e32 v18, v18, v26
	v_add_f32_e32 v18, v18, v27
	v_lshl_add_u64 v[28:29], s[30:31], 0, v[28:29]
	v_lshl_add_u64 v[16:17], v[16:17], 2, v[28:29]
	v_readlane_b32 s41, v233, 11
	v_readlane_b32 s42, v233, 12
	v_readlane_b32 s43, v233, 13
	v_readlane_b32 s44, v233, 14
	v_readlane_b32 s45, v233, 15
	v_readlane_b32 s48, v233, 18
	v_readlane_b32 s49, v233, 19
	v_readlane_b32 s50, v233, 20
	v_readlane_b32 s51, v233, 21
	v_readlane_b32 s52, v233, 22
	v_readlane_b32 s53, v233, 23
	v_readlane_b32 s54, v233, 24
	v_readlane_b32 s55, v233, 25
	v_readlane_b32 s25, v233, 1
	v_readlane_b32 s26, v233, 2
	v_readlane_b32 s27, v233, 3
	v_readlane_b32 s28, v233, 4
	v_readlane_b32 s29, v233, 5
	s_waitcnt vmcnt(0)
	v_add_f32_e32 v18, v18, v30
	global_store_dword v[16:17], v18, off
	s_branch .LBB0_5

; __device__ __forceinline__ s16x4 vtr(LAS unsigned char* p) { return __builtin_bit_cast(s16x4, __builtin_amdgcn_ds_read_tr16_b64_v4i16((LAS v4i16_t*)p)); }
; #define MFMA32(a, b, c) __builtin_amdgcn_mfma_f32_32x32x16_bf16((a), (b), (c), 0, 0, 0)
; #define WAITV_BAR(N) asm volatile("s_waitcnt vmcnt(" #N ") lgkmcnt(0)\n\ts_barrier" ::: "memory")
; #define GA(P, g, k) do { sa_ += P[4 * (g)]; sb_ += P[4 * (g) + 1]; sa_ += P[4 * (g) + 2]; sb_ += P[4 * (g) + 3]; \
;         pw_[k][2 * ((g) & 1)] = cvt_pk_bf16(P[4 * (g)], P[4 * (g) + 1]); pw_[k][2 * ((g) & 1) + 1] = cvt_pk_bf16(P[4 * (g) + 2], P[4 * (g) + 3]); } while (0)
; __device__ __forceinline__ void diff_unit(LAS unsigned char* lds, const bf16_t* __restrict__ u, bf16_t* __restrict__ yz, float* __restrict__ oscr, const unsigned* __restrict__ kb, int b, int h, int qb, float lam, float slope2, const float* __restrict__ gsub, float out_scale) {
;     ...
;         {
;             float sa_ = 0.f, sb_ = 0.f;
;             GA(fin0, 0, 0); GA(fin0, 1, 0); GA(fin0, 2, 1); GA(fin0, 3, 1); GA(fin1, 0, 2); GA(fin1, 1, 2); GA(fin1, 2, 3); GA(fin1, 3, 3);
;             l += sa_ + sb_;
;             const unsigned vso = (unsigned)vs_last * 16384u;
; #pragma unroll
;             for (int ks = 0; ks < 4; ++ks)
; #pragma unroll
;                 for (int c = 0; c < 4; ++c) {
;                     const s16x4 a0_ = vtr(lds + vso + vba[c][0] + ks * 4096), a1_ = vtr(lds + vso + vba[c][1] + ks * 4096);
;                     const bf16x8 v_ = (bf16x8){a0_[0], a0_[1], a0_[2], a0_[3], a1_[0], a1_[1], a1_[2], a1_[3]};
;                     o[c] = MFMA32(v_, __builtin_bit_cast(bf16x8, pw_[ks]), o[c]); }
;         }
;         WAITV_BAR(0);
;     ...
;         const float ltot = l + __shfl_xor(l, 32), inv = 1.0f / ltot;
.LBB0_286:
	s_waitcnt lgkmcnt(0)
	s_add_i32 s2, s10, 0
	s_mov_b64 s[8:9], -1
	v_add_u32_e32 v82, s2, v146
	v_add_u32_e32 v83, s2, v147
	v_add_u32_e32 v84, s2, v148
	v_add_u32_e32 v85, s2, v149
	v_add_u32_e32 v86, s2, v150
	v_add_u32_e32 v87, s2, v151
	v_add_u32_e32 v88, s2, v152
	v_add_u32_e32 v89, s2, v153
	ds_read_b64_tr_b16 v[210:211], v82
	ds_read_b64_tr_b16 v[212:213], v83
	ds_read_b64_tr_b16 v[214:215], v84
	ds_read_b64_tr_b16 v[216:217], v85
	ds_read_b64_tr_b16 v[218:219], v86
	ds_read_b64_tr_b16 v[220:221], v87
	ds_read_b64_tr_b16 v[222:223], v88
	ds_read_b64_tr_b16 v[224:225], v89
	ds_read_b64_tr_b16 v[226:227], v82 offset:4096
	ds_read_b64_tr_b16 v[228:229], v83 offset:4096
	ds_read_b64_tr_b16 v[234:235], v84 offset:4096
	ds_read_b64_tr_b16 v[236:237], v85 offset:4096
	v_cvt_pk_bf16_f32 v194, v128, v174
	v_cvt_pk_bf16_f32 v195, v172, v176
	v_cvt_pk_bf16_f32 v196, v177, v180
	v_cvt_pk_bf16_f32 v197, v181, v183
	v_cvt_pk_bf16_f32 v198, v184, v185
	v_cvt_pk_bf16_f32 v199, v186, v188
	v_cvt_pk_bf16_f32 v200, v187, v189
	v_cvt_pk_bf16_f32 v201, v190, v191
	v_cvt_pk_bf16_f32 v202, v121, v122
	v_cvt_pk_bf16_f32 v203, v123, v124
	v_cvt_pk_bf16_f32 v204, v125, v126
	v_cvt_pk_bf16_f32 v205, v127, v129
	v_cvt_pk_bf16_f32 v206, v142, v175
	v_cvt_pk_bf16_f32 v207, v173, v178
	v_cvt_pk_bf16_f32 v208, v179, v182
	v_cvt_pk_bf16_f32 v209, v192, v193
	s_waitcnt lgkmcnt(10)
	v_mfma_f32_32x32x16_bf16 v[2:17], v[210:213], v[194:197], v[2:17]
	ds_read_b64_tr_b16 v[210:211], v86 offset:4096
	ds_read_b64_tr_b16 v[212:213], v87 offset:4096
	v_add_f32_e32 v230, v128, v172
	v_add_f32_e32 v231, v174, v176
	s_waitcnt lgkmcnt(10)
	v_mfma_f32_32x32x16_bf16 v[18:33], v[214:217], v[194:197], v[18:33]
	ds_read_b64_tr_b16 v[214:215], v88 offset:4096
	ds_read_b64_tr_b16 v[216:217], v89 offset:4096
	v_add_f32_e32 v230, v177, v230
	v_add_f32_e32 v231, v180, v231
	s_waitcnt lgkmcnt(10)
	v_mfma_f32_32x32x16_bf16 v[34:49], v[218:221], v[194:197], v[34:49]
	ds_read_b64_tr_b16 v[218:219], v82 offset:8192
	ds_read_b64_tr_b16 v[220:221], v83 offset:8192
	v_add_f32_e32 v230, v181, v230
	v_add_f32_e32 v231, v183, v231
	s_waitcnt lgkmcnt(10)
	v_mfma_f32_32x32x16_bf16 v[50:65], v[222:225], v[194:197], v[50:65]
	ds_read_b64_tr_b16 v[222:223], v84 offset:8192
	ds_read_b64_tr_b16 v[224:225], v85 offset:8192
	v_add_f32_e32 v230, v184, v230
	v_add_f32_e32 v231, v185, v231
	s_waitcnt lgkmcnt(10)
	v_mfma_f32_32x32x16_bf16 v[2:17], v[226:229], v[198:201], v[2:17]
	ds_read_b64_tr_b16 v[226:227], v86 offset:8192
	ds_read_b64_tr_b16 v[228:229], v87 offset:8192
	v_add_f32_e32 v230, v186, v230
	v_add_f32_e32 v231, v188, v231
	s_waitcnt lgkmcnt(10)
	v_mfma_f32_32x32x16_bf16 v[18:33], v[234:237], v[198:201], v[18:33]
	ds_read_b64_tr_b16 v[234:235], v88 offset:8192
	ds_read_b64_tr_b16 v[236:237], v89 offset:8192
	v_add_f32_e32 v230, v187, v230
	v_add_f32_e32 v231, v189, v231
	s_waitcnt lgkmcnt(10)
	v_mfma_f32_32x32x16_bf16 v[34:49], v[210:213], v[198:201], v[34:49]
	ds_read_b64_tr_b16 v[210:211], v82 offset:12288
	ds_read_b64_tr_b16 v[212:213], v83 offset:12288
	v_add_f32_e32 v230, v190, v230
	v_add_f32_e32 v231, v191, v231
	s_waitcnt lgkmcnt(10)
	v_mfma_f32_32x32x16_bf16 v[50:65], v[214:217], v[198:201], v[50:65]
	ds_read_b64_tr_b16 v[214:215], v84 offset:12288
	ds_read_b64_tr_b16 v[216:217], v85 offset:12288
	v_add_f32_e32 v230, v121, v230
	v_add_f32_e32 v231, v122, v231
	s_waitcnt lgkmcnt(10)
	v_mfma_f32_32x32x16_bf16 v[2:17], v[218:221], v[202:205], v[2:17]
	ds_read_b64_tr_b16 v[218:219], v86 offset:12288
	ds_read_b64_tr_b16 v[220:221], v87 offset:12288
	v_add_f32_e32 v230, v123, v230
	v_add_f32_e32 v231, v124, v231
	s_waitcnt lgkmcnt(10)
	v_mfma_f32_32x32x16_bf16 v[18:33], v[222:225], v[202:205], v[18:33]
	ds_read_b64_tr_b16 v[222:223], v88 offset:12288
	ds_read_b64_tr_b16 v[224:225], v89 offset:12288
	v_add_f32_e32 v230, v125, v230
	v_add_f32_e32 v231, v126, v231
	s_waitcnt lgkmcnt(10)
	v_mfma_f32_32x32x16_bf16 v[34:49], v[226:229], v[202:205], v[34:49]
	v_add_f32_e32 v230, v127, v230
	v_add_f32_e32 v231, v129, v231
	s_waitcnt lgkmcnt(8)
	v_mfma_f32_32x32x16_bf16 v[50:65], v[234:237], v[202:205], v[50:65]
	v_add_f32_e32 v230, v142, v230
	v_add_f32_e32 v231, v175, v231
	s_waitcnt lgkmcnt(6)
	v_mfma_f32_32x32x16_bf16 v[2:17], v[210:213], v[206:209], v[2:17]
	v_add_f32_e32 v230, v173, v230
	v_add_f32_e32 v231, v178, v231
	s_waitcnt lgkmcnt(4)
	v_mfma_f32_32x32x16_bf16 v[18:33], v[214:217], v[206:209], v[18:33]
	v_add_f32_e32 v230, v179, v230
	v_add_f32_e32 v231, v182, v231
	s_waitcnt lgkmcnt(2)
	v_mfma_f32_32x32x16_bf16 v[34:49], v[218:221], v[206:209], v[34:49]
	v_add_f32_e32 v230, v192, v230
	v_add_f32_e32 v231, v193, v231
	s_waitcnt vmcnt(0) lgkmcnt(0)
	s_barrier
	v_mfma_f32_32x32x16_bf16 v[50:65], v[222:225], v[206:209], v[50:65]
	v_add_f32_e32 v0, v230, v231
	v_add_f32_e32 v0, v118, v0
	ds_bpermute_b32 v66, v143, v0
	s_waitcnt lgkmcnt(0)
	v_add_f32_e32 v0, v0, v66
	v_div_scale_f32 v66, s[2:3], v0, v0, 1.0
	v_rcp_f32_e32 v67, v66
	s_nop 0
	v_fma_f32 v68, -v66, v67, 1.0
	v_fmac_f32_e32 v67, v68, v67
	v_div_scale_f32 v68, vcc, 1.0, v0, 1.0
	v_mul_f32_e32 v69, v68, v67
	v_fma_f32 v70, -v66, v69, v68
	v_fmac_f32_e32 v69, v70, v67
	v_fma_f32 v66, -v66, v69, v68
	v_div_fmas_f32 v66, v66, v67, v69
	v_div_fixup_f32 v0, v66, v0, 1.0
	v_mov_b32_e32 v66, v140
	s_and_b64 vcc, exec, s[30:31]
	v_ashrrev_i32_e32 v67, 31, v66
	v_lshlrev_b64 v[66:67], 8, v[66:67]
	v_lshl_add_u64 v[132:133], s[86:87], 0, v[66:67]
	s_cbranch_vccnz .LBB0_288
	s_andn2_b64 vcc, exec, s[8:9]
	s_cbranch_vccnz .LBB0_219
	s_branch .LBB0_289
